# Q up-proj rope tiles: second cos/sin load pair of each row issued with the first (one wait per row instead of two)
# baseline (speedup 1.0000x reference)
; __device__ __forceinline__ unsigned cvt_pk_bf16(float lo, float hi) { const cvt_f32x2 v = {lo, hi}; const cvt_bf16x2 b = __builtin_convertvector(v, cvt_bf16x2); return __builtin_bit_cast(unsigned, b); }
; #define EPI_ROWLOOP _Pragma("unroll") for (int ai = 0; ai < 2; ++ai) _Pragma("unroll") for (int m = 0; m < 4; ++m)
;     __device__ __forceinline__ void operator()(const f32x4 (&acc)[2][2][4][2], const Unit& u, int wr, int wc, int fr, int fq) const {
;     ...
;             EPI_ROWLOOP { const int r = row0 + ai * HALF + m * 16; const f32x4 pq = part[r]; const float rs = __builtin_amdgcn_rsqf(((pq[0] + pq[1]) + (pq[2] + pq[3])) * (1.0f / 256.0f) + EP_EPS) * qscale;
;                 const float* t = ropecs + ((size_t)pos_of_row(r) * 32 + 8 * fq) * 2;
;                 bf16_t* rowp = QR + (size_t)r * 512 + (4 * (pn - 4) + wc) * 64 + 8 * fq;
; #pragma unroll
;                 for (int n = 0; n < 2; ++n) { f32x4 a = acc[ai][0][m][n], b = acc[ai][1][m][n]; rope4(a, b, t + 8 * n); a = a * rs; b = b * rs;
;                     *(u32x2*)(rowp + 4 * n) = (u32x2){cvt_pk_bf16(a[0], a[1]), cvt_pk_bf16(a[2], a[3])}; *(u32x2*)(rowp + 32 + 4 * n) = (u32x2){cvt_pk_bf16(b[0], b[1]), cvt_pk_bf16(b[2], b[3])};
;                     asm volatile("" ::: "memory"); } }
.LBB0_541:
	v_lshl_add_u64 v[158:159], v[156:157], 4, s[50:51]
	global_load_dwordx4 v[128:131], v[158:159], off
	v_cmp_lt_i32_e32 vcc, s81, v156
	s_and_saveexec_b64 s[60:61], vcc
	s_xor_b64 s[60:61], exec, s[60:61]
	s_cmp_lt_u32 s59, 0x10010
	v_add_u32_e32 v140, 0xffff0000, v156
	s_cselect_b64 vcc, -1, 0
	v_cndmask_b32_e32 v140, 0, v140, vcc
	s_andn2_saveexec_b64 s[60:61], s[60:61]
	v_and_or_b32 v140, v156, s83, 16
	s_or_b64 exec, exec, s[60:61]
	v_lshlrev_b64 v[160:161], 8, v[140:141]
	v_lshl_add_u64 v[162:163], v[142:143], 0, v[160:161]
	global_load_dwordx4 v[170:173], v[162:163], off offset:16
	global_load_dwordx4 v[174:177], v[162:163], off
	global_load_dwordx4 v[184:187], v[162:163], off offset:48
	global_load_dwordx4 v[188:191], v[162:163], off offset:32
	s_waitcnt vmcnt(0)
	v_add_f32_e32 v128, v128, v129
	v_add_f32_e32 v129, v130, v131
	v_add_f32_e32 v128, v128, v129
	v_fmamk_f32 v128, v128, 0x3b800000, v169
	v_rsq_f32_e32 v130, v128
	s_add_i32 s12, s68, s58
	v_lshlrev_b64 v[128:129], 10, v[156:157]
	v_lshl_add_u64 v[160:161], s[12:13], 1, v[144:145]
	v_lshl_add_u64 v[178:179], v[160:161], 0, v[128:129]
	v_mul_f32_e32 v140, 0x3dd53b94, v130
	v_mov_b32_e32 v128, v171
	v_mov_b32_e32 v129, v173
	v_mov_b32_e32 v130, v175
	v_mov_b32_e32 v131, v177
	v_mov_b32_e32 v175, v176
	v_mov_b32_e32 v171, v172
	v_pk_mul_f32 v[172:173], v[118:119], v[128:129]
	v_pk_mul_f32 v[176:177], v[116:117], v[130:131]
	v_pk_mul_f32 v[180:181], v[118:119], v[170:171]
	v_pk_mul_f32 v[182:183], v[116:117], v[174:175]
	v_pk_fma_f32 v[174:175], v[120:121], v[174:175], v[176:177] neg_lo:[0,0,1] neg_hi:[0,0,1]
	v_pk_fma_f32 v[170:171], v[122:123], v[170:171], v[172:173] neg_lo:[0,0,1] neg_hi:[0,0,1]
	v_pk_fma_f32 v[130:131], v[120:121], v[130:131], v[182:183]
	v_pk_fma_f32 v[128:129], v[122:123], v[128:129], v[180:181]
	v_pk_mul_f32 v[170:171], v[140:141], v[170:171] op_sel_hi:[0,1]
	v_pk_mul_f32 v[172:173], v[140:141], v[174:175] op_sel_hi:[0,1]
	v_pk_mul_f32 v[128:129], v[140:141], v[128:129] op_sel_hi:[0,1]
	v_pk_mul_f32 v[130:131], v[140:141], v[130:131] op_sel_hi:[0,1]
	v_cvt_pk_bf16_f32 v172, v172, v173
	v_cvt_pk_bf16_f32 v173, v170, v171
	v_cvt_pk_bf16_f32 v130, v130, v131
	v_cvt_pk_bf16_f32 v131, v128, v129
	global_store_dwordx2 v[178:179], v[172:173], off
	global_store_dwordx2 v[178:179], v[130:131], off offset:64
	s_nop 1
	v_or_b32_e32 v162, 16, v156
	v_ashrrev_i32_e32 v163, 31, v162
	v_cmp_lt_i32_e32 vcc, s81, v162
	v_mov_b32_e32 v128, v184
	v_mov_b32_e32 v129, v185
	v_mov_b32_e32 v130, v186
	v_mov_b32_e32 v131, v187
	v_mov_b32_e32 v170, v188
	v_mov_b32_e32 v171, v189
	v_mov_b32_e32 v172, v190
	v_mov_b32_e32 v173, v191
	v_mov_b32_e32 v174, v129
	v_mov_b32_e32 v175, v131
	v_mov_b32_e32 v176, v171
	v_mov_b32_e32 v177, v173
	v_mov_b32_e32 v171, v172
	v_mov_b32_e32 v129, v130
	v_pk_mul_f32 v[130:131], v[114:115], v[174:175]
	v_pk_mul_f32 v[172:173], v[112:113], v[176:177]
	v_pk_mul_f32 v[180:181], v[114:115], v[128:129]
	v_pk_mul_f32 v[182:183], v[112:113], v[170:171]
	v_pk_fma_f32 v[170:171], v[124:125], v[170:171], v[172:173] neg_lo:[0,0,1] neg_hi:[0,0,1]
	v_pk_fma_f32 v[128:129], v[126:127], v[128:129], v[130:131] neg_lo:[0,0,1] neg_hi:[0,0,1]
	v_pk_fma_f32 v[130:131], v[124:125], v[176:177], v[182:183]
	v_pk_fma_f32 v[172:173], v[126:127], v[174:175], v[180:181]
	v_pk_mul_f32 v[128:129], v[140:141], v[128:129] op_sel_hi:[0,1]
	v_pk_mul_f32 v[170:171], v[140:141], v[170:171] op_sel_hi:[0,1]
	v_pk_mul_f32 v[172:173], v[140:141], v[172:173] op_sel_hi:[0,1]
	v_pk_mul_f32 v[130:131], v[140:141], v[130:131] op_sel_hi:[0,1]
	v_cvt_pk_bf16_f32 v170, v170, v171
	v_cvt_pk_bf16_f32 v171, v128, v129
	v_cvt_pk_bf16_f32 v128, v130, v131
	v_cvt_pk_bf16_f32 v129, v172, v173
	global_store_dwordx2 v[178:179], v[170:171], off offset:8
	global_store_dwordx2 v[178:179], v[128:129], off offset:72
	v_lshl_add_u64 v[128:129], v[162:163], 4, s[50:51]
	global_load_dwordx4 v[128:131], v[128:129], off
	s_and_saveexec_b64 s[60:61], vcc
	s_xor_b64 s[60:61], exec, s[60:61]
	v_add_u32_e32 v140, 0xffff0010, v156
	v_cmp_gt_u32_e32 vcc, s82, v162
	s_nop 1
	v_cndmask_b32_e32 v140, 0, v140, vcc
	s_andn2_saveexec_b64 s[60:61], s[60:61]
	v_and_b32_e32 v140, 0x7df, v162
	v_add_u32_e32 v140, 16, v140
	s_or_b64 exec, exec, s[60:61]
	v_lshlrev_b64 v[170:171], 8, v[140:141]
	v_lshl_add_u64 v[178:179], v[142:143], 0, v[170:171]
	global_load_dwordx4 v[170:173], v[178:179], off offset:16
	global_load_dwordx4 v[174:177], v[178:179], off
	global_load_dwordx4 v[184:187], v[178:179], off offset:48
	global_load_dwordx4 v[188:191], v[178:179], off offset:32
	s_waitcnt vmcnt(0)
; __device__ __forceinline__ unsigned cvt_pk_bf16(float lo, float hi) { const cvt_f32x2 v = {lo, hi}; const cvt_bf16x2 b = __builtin_convertvector(v, cvt_bf16x2); return __builtin_bit_cast(unsigned, b); }
; #define EPI_ROWLOOP _Pragma("unroll") for (int ai = 0; ai < 2; ++ai) _Pragma("unroll") for (int m = 0; m < 4; ++m)
;     __device__ __forceinline__ void operator()(const f32x4 (&acc)[2][2][4][2], const Unit& u, int wr, int wc, int fr, int fq) const {
;     ...
;             EPI_ROWLOOP { const int r = row0 + ai * HALF + m * 16; const f32x4 pq = part[r]; const float rs = __builtin_amdgcn_rsqf(((pq[0] + pq[1]) + (pq[2] + pq[3])) * (1.0f / 256.0f) + EP_EPS) * qscale;
;                 const float* t = ropecs + ((size_t)pos_of_row(r) * 32 + 8 * fq) * 2;
;                 bf16_t* rowp = QR + (size_t)r * 512 + (4 * (pn - 4) + wc) * 64 + 8 * fq;
; #pragma unroll
;                 for (int n = 0; n < 2; ++n) { f32x4 a = acc[ai][0][m][n], b = acc[ai][1][m][n]; rope4(a, b, t + 8 * n); a = a * rs; b = b * rs;
;                     *(u32x2*)(rowp + 4 * n) = (u32x2){cvt_pk_bf16(a[0], a[1]), cvt_pk_bf16(a[2], a[3])}; *(u32x2*)(rowp + 32 + 4 * n) = (u32x2){cvt_pk_bf16(b[0], b[1]), cvt_pk_bf16(b[2], b[3])};
;                     asm volatile("" ::: "memory"); } }
	v_add_f32_e32 v128, v128, v129
	v_add_f32_e32 v129, v130, v131
	v_add_f32_e32 v128, v128, v129
	v_fmamk_f32 v128, v128, 0x3b800000, v169
	v_rsq_f32_e32 v130, v128
	v_lshlrev_b64 v[128:129], 10, v[162:163]
	v_lshl_add_u64 v[180:181], v[160:161], 0, v[128:129]
	v_mul_f32_e32 v140, 0x3dd53b94, v130
	v_mov_b32_e32 v128, v171
	v_mov_b32_e32 v129, v173
	v_mov_b32_e32 v130, v175
	v_mov_b32_e32 v131, v177
	v_mov_b32_e32 v175, v176
	v_mov_b32_e32 v171, v172
	v_pk_mul_f32 v[162:163], v[102:103], v[128:129]
	v_pk_mul_f32 v[172:173], v[100:101], v[130:131]
	v_pk_mul_f32 v[176:177], v[102:103], v[170:171]
	v_pk_mul_f32 v[182:183], v[100:101], v[174:175]
	v_pk_fma_f32 v[172:173], v[108:109], v[174:175], v[172:173] neg_lo:[0,0,1] neg_hi:[0,0,1]
	v_pk_fma_f32 v[162:163], v[110:111], v[170:171], v[162:163] neg_lo:[0,0,1] neg_hi:[0,0,1]
	v_pk_fma_f32 v[130:131], v[108:109], v[130:131], v[182:183]
	v_pk_fma_f32 v[128:129], v[110:111], v[128:129], v[176:177]
	v_pk_mul_f32 v[162:163], v[140:141], v[162:163] op_sel_hi:[0,1]
	v_pk_mul_f32 v[170:171], v[140:141], v[172:173] op_sel_hi:[0,1]
	v_pk_mul_f32 v[128:129], v[140:141], v[128:129] op_sel_hi:[0,1]
	v_pk_mul_f32 v[130:131], v[140:141], v[130:131] op_sel_hi:[0,1]
	v_cvt_pk_bf16_f32 v170, v170, v171
	v_cvt_pk_bf16_f32 v171, v162, v163
	v_cvt_pk_bf16_f32 v130, v130, v131
	v_cvt_pk_bf16_f32 v131, v128, v129
	global_store_dwordx2 v[180:181], v[170:171], off
	global_store_dwordx2 v[180:181], v[130:131], off offset:64
	s_nop 1
	v_or_b32_e32 v162, 32, v156
	v_ashrrev_i32_e32 v163, 31, v162
	v_cmp_lt_i32_e32 vcc, s81, v162
	v_mov_b32_e32 v128, v184
	v_mov_b32_e32 v129, v185
	v_mov_b32_e32 v130, v186
	v_mov_b32_e32 v131, v187
	v_mov_b32_e32 v170, v188
	v_mov_b32_e32 v171, v189
	v_mov_b32_e32 v172, v190
	v_mov_b32_e32 v173, v191
	v_mov_b32_e32 v174, v129
	v_mov_b32_e32 v175, v131
	v_mov_b32_e32 v176, v171
	v_mov_b32_e32 v177, v173
	v_mov_b32_e32 v171, v172
	v_mov_b32_e32 v129, v130
	v_pk_mul_f32 v[130:131], v[98:99], v[174:175]
	v_pk_mul_f32 v[172:173], v[96:97], v[176:177]
	v_pk_mul_f32 v[178:179], v[98:99], v[128:129]
	v_pk_mul_f32 v[182:183], v[96:97], v[170:171]
	v_pk_fma_f32 v[170:171], v[104:105], v[170:171], v[172:173] neg_lo:[0,0,1] neg_hi:[0,0,1]
	v_pk_fma_f32 v[128:129], v[106:107], v[128:129], v[130:131] neg_lo:[0,0,1] neg_hi:[0,0,1]
	v_pk_fma_f32 v[130:131], v[104:105], v[176:177], v[182:183]
	v_pk_fma_f32 v[172:173], v[106:107], v[174:175], v[178:179]
	v_pk_mul_f32 v[128:129], v[140:141], v[128:129] op_sel_hi:[0,1]
	v_pk_mul_f32 v[170:171], v[140:141], v[170:171] op_sel_hi:[0,1]
	v_pk_mul_f32 v[172:173], v[140:141], v[172:173] op_sel_hi:[0,1]
	v_pk_mul_f32 v[130:131], v[140:141], v[130:131] op_sel_hi:[0,1]
	v_cvt_pk_bf16_f32 v170, v170, v171
	v_cvt_pk_bf16_f32 v171, v128, v129
	v_cvt_pk_bf16_f32 v128, v130, v131
	v_cvt_pk_bf16_f32 v129, v172, v173
	global_store_dwordx2 v[180:181], v[170:171], off offset:8
	global_store_dwordx2 v[180:181], v[128:129], off offset:72
	v_lshl_add_u64 v[128:129], v[162:163], 4, s[50:51]
	global_load_dwordx4 v[128:131], v[128:129], off
	s_and_saveexec_b64 s[60:61], vcc
	s_xor_b64 s[60:61], exec, s[60:61]
	v_add_u32_e32 v140, 0xffff0020, v156
	v_cmp_gt_u32_e32 vcc, s82, v162
	s_nop 1
	v_cndmask_b32_e32 v140, 0, v140, vcc
	s_andn2_saveexec_b64 s[60:61], s[60:61]
	v_and_or_b32 v140, v162, s84, 16
	s_or_b64 exec, exec, s[60:61]
	v_lshlrev_b64 v[170:171], 8, v[140:141]
	v_lshl_add_u64 v[178:179], v[142:143], 0, v[170:171]
	global_load_dwordx4 v[170:173], v[178:179], off offset:16
	global_load_dwordx4 v[174:177], v[178:179], off
	global_load_dwordx4 v[184:187], v[178:179], off offset:48
	global_load_dwordx4 v[188:191], v[178:179], off offset:32
	s_waitcnt vmcnt(0)
	v_add_f32_e32 v128, v128, v129
	v_add_f32_e32 v129, v130, v131
	v_add_f32_e32 v128, v128, v129
	v_fmamk_f32 v128, v128, 0x3b800000, v169
	v_rsq_f32_e32 v130, v128
	v_lshlrev_b64 v[128:129], 10, v[162:163]
	v_lshl_add_u64 v[180:181], v[160:161], 0, v[128:129]
	v_mul_f32_e32 v140, 0x3dd53b94, v130
	v_mov_b32_e32 v128, v171
	v_mov_b32_e32 v129, v173
	v_mov_b32_e32 v130, v175
	v_mov_b32_e32 v131, v177
	v_mov_b32_e32 v175, v176
	v_mov_b32_e32 v171, v172
	v_pk_mul_f32 v[162:163], v[86:87], v[128:129]
	v_pk_mul_f32 v[172:173], v[84:85], v[130:131]
	v_pk_mul_f32 v[176:177], v[86:87], v[170:171]
	v_pk_mul_f32 v[182:183], v[84:85], v[174:175]
	v_pk_fma_f32 v[172:173], v[92:93], v[174:175], v[172:173] neg_lo:[0,0,1] neg_hi:[0,0,1]
	v_pk_fma_f32 v[162:163], v[94:95], v[170:171], v[162:163] neg_lo:[0,0,1] neg_hi:[0,0,1]
	v_pk_fma_f32 v[130:131], v[92:93], v[130:131], v[182:183]
	v_pk_fma_f32 v[128:129], v[94:95], v[128:129], v[176:177]
	v_pk_mul_f32 v[162:163], v[140:141], v[162:163] op_sel_hi:[0,1]
	v_pk_mul_f32 v[170:171], v[140:141], v[172:173] op_sel_hi:[0,1]
	v_pk_mul_f32 v[128:129], v[140:141], v[128:129] op_sel_hi:[0,1]
	v_pk_mul_f32 v[130:131], v[140:141], v[130:131] op_sel_hi:[0,1]
	v_cvt_pk_bf16_f32 v170, v170, v171
	v_cvt_pk_bf16_f32 v171, v162, v163
	v_cvt_pk_bf16_f32 v130, v130, v131
	v_cvt_pk_bf16_f32 v131, v128, v129
	global_store_dwordx2 v[180:181], v[170:171], off
	global_store_dwordx2 v[180:181], v[130:131], off offset:64
	s_nop 1
	v_or_b32_e32 v162, 48, v156
	v_ashrrev_i32_e32 v163, 31, v162
	v_cmp_lt_i32_e32 vcc, s81, v162
	v_mov_b32_e32 v128, v184
	v_mov_b32_e32 v129, v185
	v_mov_b32_e32 v130, v186
	v_mov_b32_e32 v131, v187
	v_mov_b32_e32 v170, v188
	v_mov_b32_e32 v171, v189
	v_mov_b32_e32 v172, v190
	v_mov_b32_e32 v173, v191
	v_mov_b32_e32 v174, v129
	v_mov_b32_e32 v175, v131
	v_mov_b32_e32 v176, v171
	v_mov_b32_e32 v177, v173
	v_mov_b32_e32 v171, v172
	v_mov_b32_e32 v129, v130
	v_pk_mul_f32 v[130:131], v[82:83], v[174:175]
; __device__ __forceinline__ unsigned cvt_pk_bf16(float lo, float hi) { const cvt_f32x2 v = {lo, hi}; const cvt_bf16x2 b = __builtin_convertvector(v, cvt_bf16x2); return __builtin_bit_cast(unsigned, b); }
; #define EPI_ROWLOOP _Pragma("unroll") for (int ai = 0; ai < 2; ++ai) _Pragma("unroll") for (int m = 0; m < 4; ++m)
;     __device__ __forceinline__ void operator()(const f32x4 (&acc)[2][2][4][2], const Unit& u, int wr, int wc, int fr, int fq) const {
;     ...
;             EPI_ROWLOOP { const int r = row0 + ai * HALF + m * 16; const f32x4 pq = part[r]; const float rs = __builtin_amdgcn_rsqf(((pq[0] + pq[1]) + (pq[2] + pq[3])) * (1.0f / 256.0f) + EP_EPS) * qscale;
;                 const float* t = ropecs + ((size_t)pos_of_row(r) * 32 + 8 * fq) * 2;
;                 bf16_t* rowp = QR + (size_t)r * 512 + (4 * (pn - 4) + wc) * 64 + 8 * fq;
; #pragma unroll
;                 for (int n = 0; n < 2; ++n) { f32x4 a = acc[ai][0][m][n], b = acc[ai][1][m][n]; rope4(a, b, t + 8 * n); a = a * rs; b = b * rs;
;                     *(u32x2*)(rowp + 4 * n) = (u32x2){cvt_pk_bf16(a[0], a[1]), cvt_pk_bf16(a[2], a[3])}; *(u32x2*)(rowp + 32 + 4 * n) = (u32x2){cvt_pk_bf16(b[0], b[1]), cvt_pk_bf16(b[2], b[3])};
;                     asm volatile("" ::: "memory"); } }
	v_pk_mul_f32 v[172:173], v[80:81], v[176:177]
	v_pk_mul_f32 v[178:179], v[82:83], v[128:129]
	v_pk_mul_f32 v[182:183], v[80:81], v[170:171]
	v_pk_fma_f32 v[170:171], v[88:89], v[170:171], v[172:173] neg_lo:[0,0,1] neg_hi:[0,0,1]
	v_pk_fma_f32 v[128:129], v[90:91], v[128:129], v[130:131] neg_lo:[0,0,1] neg_hi:[0,0,1]
	v_pk_fma_f32 v[130:131], v[88:89], v[176:177], v[182:183]
	v_pk_fma_f32 v[172:173], v[90:91], v[174:175], v[178:179]
	v_pk_mul_f32 v[128:129], v[140:141], v[128:129] op_sel_hi:[0,1]
	v_pk_mul_f32 v[170:171], v[140:141], v[170:171] op_sel_hi:[0,1]
	v_pk_mul_f32 v[172:173], v[140:141], v[172:173] op_sel_hi:[0,1]
	v_pk_mul_f32 v[130:131], v[140:141], v[130:131] op_sel_hi:[0,1]
	v_cvt_pk_bf16_f32 v170, v170, v171
	v_cvt_pk_bf16_f32 v171, v128, v129
	v_cvt_pk_bf16_f32 v128, v130, v131
	v_cvt_pk_bf16_f32 v129, v172, v173
	global_store_dwordx2 v[180:181], v[170:171], off offset:8
	global_store_dwordx2 v[180:181], v[128:129], off offset:72
	v_lshl_add_u64 v[128:129], v[162:163], 4, s[50:51]
	global_load_dwordx4 v[128:131], v[128:129], off
	s_and_saveexec_b64 s[60:61], vcc
	s_xor_b64 s[60:61], exec, s[60:61]
	v_add_u32_e32 v140, 0xffff0030, v156
	v_cmp_gt_u32_e32 vcc, s82, v162
	s_nop 1
	v_cndmask_b32_e32 v140, 0, v140, vcc
	s_andn2_saveexec_b64 s[60:61], s[60:61]
	v_and_b32_e32 v140, 0x7ff, v162
	v_add_u32_e32 v140, 16, v140
	s_or_b64 exec, exec, s[60:61]
	v_lshlrev_b64 v[170:171], 8, v[140:141]
	v_lshl_add_u64 v[178:179], v[142:143], 0, v[170:171]
	global_load_dwordx4 v[170:173], v[178:179], off offset:16
	global_load_dwordx4 v[174:177], v[178:179], off
	global_load_dwordx4 v[184:187], v[178:179], off offset:48
	global_load_dwordx4 v[188:191], v[178:179], off offset:32
	s_waitcnt vmcnt(0)
	v_add_f32_e32 v128, v128, v129
	v_add_f32_e32 v129, v130, v131
	v_add_f32_e32 v128, v128, v129
	v_fmamk_f32 v128, v128, 0x3b800000, v169
	v_rsq_f32_e32 v130, v128
	v_lshlrev_b64 v[128:129], 10, v[162:163]
	v_lshl_add_u64 v[162:163], v[160:161], 0, v[128:129]
	s_mov_b32 s12, 0xff7f
	v_mul_f32_e32 v140, 0x3dd53b94, v130
	v_cmp_lt_i32_e32 vcc, s12, v156
	v_mov_b32_e32 v128, v171
	v_mov_b32_e32 v129, v173
	v_mov_b32_e32 v130, v175
	v_mov_b32_e32 v131, v177
	v_mov_b32_e32 v175, v176
	v_mov_b32_e32 v171, v172
	v_pk_mul_f32 v[172:173], v[70:71], v[128:129]
	v_pk_mul_f32 v[176:177], v[68:69], v[130:131]
	v_pk_mul_f32 v[180:181], v[70:71], v[170:171]
	v_pk_mul_f32 v[182:183], v[68:69], v[174:175]
	v_pk_fma_f32 v[174:175], v[76:77], v[174:175], v[176:177] neg_lo:[0,0,1] neg_hi:[0,0,1]
	v_pk_fma_f32 v[170:171], v[78:79], v[170:171], v[172:173] neg_lo:[0,0,1] neg_hi:[0,0,1]
	v_pk_fma_f32 v[130:131], v[76:77], v[130:131], v[182:183]
	v_pk_fma_f32 v[128:129], v[78:79], v[128:129], v[180:181]
	v_pk_mul_f32 v[170:171], v[140:141], v[170:171] op_sel_hi:[0,1]
	v_pk_mul_f32 v[172:173], v[140:141], v[174:175] op_sel_hi:[0,1]
	v_pk_mul_f32 v[128:129], v[140:141], v[128:129] op_sel_hi:[0,1]
	v_pk_mul_f32 v[130:131], v[140:141], v[130:131] op_sel_hi:[0,1]
	v_cvt_pk_bf16_f32 v172, v172, v173
	v_cvt_pk_bf16_f32 v173, v170, v171
	v_cvt_pk_bf16_f32 v130, v130, v131
	v_cvt_pk_bf16_f32 v131, v128, v129
	global_store_dwordx2 v[162:163], v[172:173], off
	global_store_dwordx2 v[162:163], v[130:131], off offset:64
	s_nop 1
	v_mov_b32_e32 v128, v184
	v_mov_b32_e32 v129, v185
	v_mov_b32_e32 v130, v186
	v_mov_b32_e32 v131, v187
	v_mov_b32_e32 v170, v188
	v_mov_b32_e32 v171, v189
	v_mov_b32_e32 v172, v190
	v_mov_b32_e32 v173, v191
	v_mov_b32_e32 v174, v129
	v_mov_b32_e32 v175, v131
	v_mov_b32_e32 v176, v171
	v_mov_b32_e32 v177, v173
	v_mov_b32_e32 v171, v172
	v_mov_b32_e32 v129, v130
	v_pk_mul_f32 v[130:131], v[66:67], v[174:175]
	v_pk_mul_f32 v[172:173], v[64:65], v[176:177]
	v_pk_mul_f32 v[178:179], v[66:67], v[128:129]
	v_pk_mul_f32 v[180:181], v[64:65], v[170:171]
	v_pk_fma_f32 v[170:171], v[72:73], v[170:171], v[172:173] neg_lo:[0,0,1] neg_hi:[0,0,1]
	v_pk_fma_f32 v[128:129], v[74:75], v[128:129], v[130:131] neg_lo:[0,0,1] neg_hi:[0,0,1]
	v_pk_fma_f32 v[130:131], v[72:73], v[176:177], v[180:181]
	v_pk_fma_f32 v[172:173], v[74:75], v[174:175], v[178:179]
	v_pk_mul_f32 v[128:129], v[140:141], v[128:129] op_sel_hi:[0,1]
	v_pk_mul_f32 v[170:171], v[140:141], v[170:171] op_sel_hi:[0,1]
	v_pk_mul_f32 v[172:173], v[140:141], v[172:173] op_sel_hi:[0,1]
	v_pk_mul_f32 v[130:131], v[140:141], v[130:131] op_sel_hi:[0,1]
	v_cvt_pk_bf16_f32 v170, v170, v171
	v_cvt_pk_bf16_f32 v171, v128, v129
	v_cvt_pk_bf16_f32 v128, v130, v131
	v_cvt_pk_bf16_f32 v129, v172, v173
	global_store_dwordx2 v[162:163], v[170:171], off offset:8
	global_store_dwordx2 v[162:163], v[128:129], off offset:72
	global_load_dwordx4 v[128:131], v[158:159], off offset:2048
	v_add_u32_e32 v162, 0x80, v156
	v_ashrrev_i32_e32 v163, 31, v162
	s_and_saveexec_b64 s[60:61], vcc
	s_xor_b64 s[60:61], exec, s[60:61]
	v_add_u32_e32 v140, 0xffff0080, v156
	v_cmp_gt_u32_e32 vcc, s82, v162
	s_nop 1
	v_cndmask_b32_e32 v140, 0, v140, vcc
	s_andn2_saveexec_b64 s[60:61], s[60:61]
	v_and_or_b32 v140, v162, s83, 16
	s_or_b64 exec, exec, s[60:61]
	v_lshlrev_b64 v[170:171], 8, v[140:141]
	v_lshl_add_u64 v[178:179], v[142:143], 0, v[170:171]
	global_load_dwordx4 v[170:173], v[178:179], off offset:16
	global_load_dwordx4 v[174:177], v[178:179], off
	global_load_dwordx4 v[184:187], v[178:179], off offset:48
	global_load_dwordx4 v[188:191], v[178:179], off offset:32
	s_waitcnt vmcnt(0)
; __device__ __forceinline__ unsigned cvt_pk_bf16(float lo, float hi) { const cvt_f32x2 v = {lo, hi}; const cvt_bf16x2 b = __builtin_convertvector(v, cvt_bf16x2); return __builtin_bit_cast(unsigned, b); }
; #define EPI_ROWLOOP _Pragma("unroll") for (int ai = 0; ai < 2; ++ai) _Pragma("unroll") for (int m = 0; m < 4; ++m)
;     __device__ __forceinline__ void operator()(const f32x4 (&acc)[2][2][4][2], const Unit& u, int wr, int wc, int fr, int fq) const {
;     ...
;             EPI_ROWLOOP { const int r = row0 + ai * HALF + m * 16; const f32x4 pq = part[r]; const float rs = __builtin_amdgcn_rsqf(((pq[0] + pq[1]) + (pq[2] + pq[3])) * (1.0f / 256.0f) + EP_EPS) * qscale;
;                 const float* t = ropecs + ((size_t)pos_of_row(r) * 32 + 8 * fq) * 2;
;                 bf16_t* rowp = QR + (size_t)r * 512 + (4 * (pn - 4) + wc) * 64 + 8 * fq;
; #pragma unroll
;                 for (int n = 0; n < 2; ++n) { f32x4 a = acc[ai][0][m][n], b = acc[ai][1][m][n]; rope4(a, b, t + 8 * n); a = a * rs; b = b * rs;
;                     *(u32x2*)(rowp + 4 * n) = (u32x2){cvt_pk_bf16(a[0], a[1]), cvt_pk_bf16(a[2], a[3])}; *(u32x2*)(rowp + 32 + 4 * n) = (u32x2){cvt_pk_bf16(b[0], b[1]), cvt_pk_bf16(b[2], b[3])};
;                     asm volatile("" ::: "memory"); } }
	v_add_f32_e32 v128, v128, v129
	v_add_f32_e32 v129, v130, v131
	v_add_f32_e32 v128, v128, v129
	v_fmamk_f32 v128, v128, 0x3b800000, v169
	v_rsq_f32_e32 v130, v128
	v_lshlrev_b64 v[128:129], 10, v[162:163]
	v_lshl_add_u64 v[162:163], v[160:161], 0, v[128:129]
	s_mov_b32 s12, 0xff6f
	v_mul_f32_e32 v140, 0x3dd53b94, v130
	v_cmp_lt_i32_e32 vcc, s12, v156
	v_mov_b32_e32 v128, v171
	v_mov_b32_e32 v129, v173
	v_mov_b32_e32 v130, v175
	v_mov_b32_e32 v131, v177
	v_mov_b32_e32 v175, v176
	v_mov_b32_e32 v171, v172
	v_pk_mul_f32 v[172:173], v[54:55], v[128:129]
	v_pk_mul_f32 v[176:177], v[52:53], v[130:131]
	v_pk_mul_f32 v[180:181], v[54:55], v[170:171]
	v_pk_mul_f32 v[182:183], v[52:53], v[174:175]
	v_pk_fma_f32 v[174:175], v[60:61], v[174:175], v[176:177] neg_lo:[0,0,1] neg_hi:[0,0,1]
	v_pk_fma_f32 v[170:171], v[62:63], v[170:171], v[172:173] neg_lo:[0,0,1] neg_hi:[0,0,1]
	v_pk_fma_f32 v[130:131], v[60:61], v[130:131], v[182:183]
	v_pk_fma_f32 v[128:129], v[62:63], v[128:129], v[180:181]
	v_pk_mul_f32 v[170:171], v[140:141], v[170:171] op_sel_hi:[0,1]
	v_pk_mul_f32 v[172:173], v[140:141], v[174:175] op_sel_hi:[0,1]
	v_pk_mul_f32 v[128:129], v[140:141], v[128:129] op_sel_hi:[0,1]
	v_pk_mul_f32 v[130:131], v[140:141], v[130:131] op_sel_hi:[0,1]
	v_cvt_pk_bf16_f32 v172, v172, v173
	v_cvt_pk_bf16_f32 v173, v170, v171
	v_cvt_pk_bf16_f32 v130, v130, v131
	v_cvt_pk_bf16_f32 v131, v128, v129
	global_store_dwordx2 v[162:163], v[172:173], off
	global_store_dwordx2 v[162:163], v[130:131], off offset:64
	s_nop 1
	v_mov_b32_e32 v128, v184
	v_mov_b32_e32 v129, v185
	v_mov_b32_e32 v130, v186
	v_mov_b32_e32 v131, v187
	v_mov_b32_e32 v170, v188
	v_mov_b32_e32 v171, v189
	v_mov_b32_e32 v172, v190
	v_mov_b32_e32 v173, v191
	v_mov_b32_e32 v174, v129
	v_mov_b32_e32 v175, v131
	v_mov_b32_e32 v176, v171
	v_mov_b32_e32 v177, v173
	v_mov_b32_e32 v171, v172
	v_mov_b32_e32 v129, v130
	v_pk_mul_f32 v[130:131], v[50:51], v[174:175]
	v_pk_mul_f32 v[172:173], v[48:49], v[176:177]
	v_pk_mul_f32 v[178:179], v[50:51], v[128:129]
	v_pk_mul_f32 v[180:181], v[48:49], v[170:171]
	v_pk_fma_f32 v[170:171], v[56:57], v[170:171], v[172:173] neg_lo:[0,0,1] neg_hi:[0,0,1]
	v_pk_fma_f32 v[128:129], v[58:59], v[128:129], v[130:131] neg_lo:[0,0,1] neg_hi:[0,0,1]
	v_pk_fma_f32 v[130:131], v[56:57], v[176:177], v[180:181]
	v_pk_fma_f32 v[172:173], v[58:59], v[174:175], v[178:179]
	v_pk_mul_f32 v[128:129], v[140:141], v[128:129] op_sel_hi:[0,1]
	v_pk_mul_f32 v[170:171], v[140:141], v[170:171] op_sel_hi:[0,1]
	v_pk_mul_f32 v[172:173], v[140:141], v[172:173] op_sel_hi:[0,1]
	v_pk_mul_f32 v[130:131], v[140:141], v[130:131] op_sel_hi:[0,1]
	v_cvt_pk_bf16_f32 v170, v170, v171
	v_cvt_pk_bf16_f32 v171, v128, v129
	v_cvt_pk_bf16_f32 v128, v130, v131
	v_cvt_pk_bf16_f32 v129, v172, v173
	global_store_dwordx2 v[162:163], v[170:171], off offset:8
	global_store_dwordx2 v[162:163], v[128:129], off offset:72
	global_load_dwordx4 v[128:131], v[158:159], off offset:2304
	v_add_u32_e32 v162, 0x90, v156
	v_ashrrev_i32_e32 v163, 31, v162
	s_and_saveexec_b64 s[60:61], vcc
	s_xor_b64 s[60:61], exec, s[60:61]
	v_add_u32_e32 v140, 0xffff0090, v156
	v_cmp_gt_u32_e32 vcc, s82, v162
	s_nop 1
	v_cndmask_b32_e32 v140, 0, v140, vcc
	s_andn2_saveexec_b64 s[60:61], s[60:61]
	v_and_b32_e32 v140, 0x7df, v162
	v_add_u32_e32 v140, 16, v140
	s_or_b64 exec, exec, s[60:61]
	v_lshlrev_b64 v[170:171], 8, v[140:141]
	v_lshl_add_u64 v[178:179], v[142:143], 0, v[170:171]
	global_load_dwordx4 v[170:173], v[178:179], off offset:16
	global_load_dwordx4 v[174:177], v[178:179], off
	global_load_dwordx4 v[184:187], v[178:179], off offset:48
	global_load_dwordx4 v[188:191], v[178:179], off offset:32
	s_waitcnt vmcnt(0)
	v_add_f32_e32 v128, v128, v129
	v_add_f32_e32 v129, v130, v131
	v_add_f32_e32 v128, v128, v129
	v_fmamk_f32 v128, v128, 0x3b800000, v169
	v_rsq_f32_e32 v130, v128
	v_lshlrev_b64 v[128:129], 10, v[162:163]
	v_lshl_add_u64 v[162:163], v[160:161], 0, v[128:129]
	s_mov_b32 s12, 0xff5f
	v_mul_f32_e32 v140, 0x3dd53b94, v130
	v_cmp_lt_i32_e32 vcc, s12, v156
	v_mov_b32_e32 v128, v171
	v_mov_b32_e32 v129, v173
	v_mov_b32_e32 v130, v175
	v_mov_b32_e32 v131, v177
	v_mov_b32_e32 v175, v176
	v_mov_b32_e32 v171, v172
	v_pk_mul_f32 v[172:173], v[38:39], v[128:129]
	v_pk_mul_f32 v[176:177], v[36:37], v[130:131]
	v_pk_mul_f32 v[180:181], v[38:39], v[170:171]
	v_pk_mul_f32 v[182:183], v[36:37], v[174:175]
	v_pk_fma_f32 v[174:175], v[44:45], v[174:175], v[176:177] neg_lo:[0,0,1] neg_hi:[0,0,1]
	v_pk_fma_f32 v[170:171], v[46:47], v[170:171], v[172:173] neg_lo:[0,0,1] neg_hi:[0,0,1]
	v_pk_fma_f32 v[130:131], v[44:45], v[130:131], v[182:183]
	v_pk_fma_f32 v[128:129], v[46:47], v[128:129], v[180:181]
	v_pk_mul_f32 v[170:171], v[140:141], v[170:171] op_sel_hi:[0,1]
	v_pk_mul_f32 v[172:173], v[140:141], v[174:175] op_sel_hi:[0,1]
	v_pk_mul_f32 v[128:129], v[140:141], v[128:129] op_sel_hi:[0,1]
	v_pk_mul_f32 v[130:131], v[140:141], v[130:131] op_sel_hi:[0,1]
	v_cvt_pk_bf16_f32 v172, v172, v173
	v_cvt_pk_bf16_f32 v173, v170, v171
	v_cvt_pk_bf16_f32 v130, v130, v131
	v_cvt_pk_bf16_f32 v131, v128, v129
	global_store_dwordx2 v[162:163], v[172:173], off
	global_store_dwordx2 v[162:163], v[130:131], off offset:64
	s_nop 1
	v_mov_b32_e32 v128, v184
	v_mov_b32_e32 v129, v185
	v_mov_b32_e32 v130, v186
	v_mov_b32_e32 v131, v187
	v_mov_b32_e32 v170, v188
	v_mov_b32_e32 v171, v189
	v_mov_b32_e32 v172, v190
	v_mov_b32_e32 v173, v191
	v_mov_b32_e32 v174, v129
	v_mov_b32_e32 v175, v131
	v_mov_b32_e32 v176, v171
	v_mov_b32_e32 v177, v173
	v_mov_b32_e32 v171, v172
	v_mov_b32_e32 v129, v130
	v_pk_mul_f32 v[130:131], v[34:35], v[174:175]
	v_pk_mul_f32 v[172:173], v[32:33], v[176:177]
; __device__ __forceinline__ unsigned cvt_pk_bf16(float lo, float hi) { const cvt_f32x2 v = {lo, hi}; const cvt_bf16x2 b = __builtin_convertvector(v, cvt_bf16x2); return __builtin_bit_cast(unsigned, b); }
; #define EPI_ROWLOOP _Pragma("unroll") for (int ai = 0; ai < 2; ++ai) _Pragma("unroll") for (int m = 0; m < 4; ++m)
;     __device__ __forceinline__ void operator()(const f32x4 (&acc)[2][2][4][2], const Unit& u, int wr, int wc, int fr, int fq) const {
;     ...
;             EPI_ROWLOOP { const int r = row0 + ai * HALF + m * 16; const f32x4 pq = part[r]; const float rs = __builtin_amdgcn_rsqf(((pq[0] + pq[1]) + (pq[2] + pq[3])) * (1.0f / 256.0f) + EP_EPS) * qscale;
;                 const float* t = ropecs + ((size_t)pos_of_row(r) * 32 + 8 * fq) * 2;
;                 bf16_t* rowp = QR + (size_t)r * 512 + (4 * (pn - 4) + wc) * 64 + 8 * fq;
; #pragma unroll
;                 for (int n = 0; n < 2; ++n) { f32x4 a = acc[ai][0][m][n], b = acc[ai][1][m][n]; rope4(a, b, t + 8 * n); a = a * rs; b = b * rs;
;                     *(u32x2*)(rowp + 4 * n) = (u32x2){cvt_pk_bf16(a[0], a[1]), cvt_pk_bf16(a[2], a[3])}; *(u32x2*)(rowp + 32 + 4 * n) = (u32x2){cvt_pk_bf16(b[0], b[1]), cvt_pk_bf16(b[2], b[3])};
;                     asm volatile("" ::: "memory"); } }
	v_pk_mul_f32 v[178:179], v[34:35], v[128:129]
	v_pk_mul_f32 v[180:181], v[32:33], v[170:171]
	v_pk_fma_f32 v[170:171], v[40:41], v[170:171], v[172:173] neg_lo:[0,0,1] neg_hi:[0,0,1]
	v_pk_fma_f32 v[128:129], v[42:43], v[128:129], v[130:131] neg_lo:[0,0,1] neg_hi:[0,0,1]
	v_pk_fma_f32 v[130:131], v[40:41], v[176:177], v[180:181]
	v_pk_fma_f32 v[172:173], v[42:43], v[174:175], v[178:179]
	v_pk_mul_f32 v[128:129], v[140:141], v[128:129] op_sel_hi:[0,1]
	v_pk_mul_f32 v[170:171], v[140:141], v[170:171] op_sel_hi:[0,1]
	v_pk_mul_f32 v[172:173], v[140:141], v[172:173] op_sel_hi:[0,1]
	v_pk_mul_f32 v[130:131], v[140:141], v[130:131] op_sel_hi:[0,1]
	v_cvt_pk_bf16_f32 v170, v170, v171
	v_cvt_pk_bf16_f32 v171, v128, v129
	v_cvt_pk_bf16_f32 v128, v130, v131
	v_cvt_pk_bf16_f32 v129, v172, v173
	global_store_dwordx2 v[162:163], v[170:171], off offset:8
	global_store_dwordx2 v[162:163], v[128:129], off offset:72
	global_load_dwordx4 v[128:131], v[158:159], off offset:2560
	v_add_u32_e32 v162, 0xa0, v156
	v_ashrrev_i32_e32 v163, 31, v162
	s_and_saveexec_b64 s[60:61], vcc
	s_xor_b64 s[60:61], exec, s[60:61]
	v_add_u32_e32 v140, 0xffff00a0, v156
	v_cmp_gt_u32_e32 vcc, s82, v162
	s_nop 1
	v_cndmask_b32_e32 v140, 0, v140, vcc
	s_andn2_saveexec_b64 s[60:61], s[60:61]
	v_and_or_b32 v140, v162, s84, 16
	s_or_b64 exec, exec, s[60:61]
	v_lshlrev_b64 v[170:171], 8, v[140:141]
	v_lshl_add_u64 v[178:179], v[142:143], 0, v[170:171]
	global_load_dwordx4 v[170:173], v[178:179], off offset:16
	global_load_dwordx4 v[174:177], v[178:179], off
	global_load_dwordx4 v[184:187], v[178:179], off offset:48
	global_load_dwordx4 v[188:191], v[178:179], off offset:32
	s_waitcnt vmcnt(0)
	v_add_f32_e32 v128, v128, v129
	v_add_f32_e32 v129, v130, v131
	v_add_f32_e32 v128, v128, v129
	v_fmamk_f32 v128, v128, 0x3b800000, v169
	v_rsq_f32_e32 v130, v128
	v_lshlrev_b64 v[128:129], 10, v[162:163]
	v_lshl_add_u64 v[162:163], v[160:161], 0, v[128:129]
	s_mov_b32 s12, 0xff4f
	v_mul_f32_e32 v140, 0x3dd53b94, v130
	v_cmp_lt_i32_e32 vcc, s12, v156
	v_mov_b32_e32 v128, v171
	v_mov_b32_e32 v129, v173
	v_mov_b32_e32 v130, v175
	v_mov_b32_e32 v131, v177
	v_mov_b32_e32 v175, v176
	v_mov_b32_e32 v171, v172
	v_pk_mul_f32 v[172:173], v[22:23], v[128:129]
	v_pk_mul_f32 v[176:177], v[20:21], v[130:131]
	v_pk_mul_f32 v[180:181], v[22:23], v[170:171]
	v_pk_mul_f32 v[182:183], v[20:21], v[174:175]
	v_pk_fma_f32 v[174:175], v[28:29], v[174:175], v[176:177] neg_lo:[0,0,1] neg_hi:[0,0,1]
	v_pk_fma_f32 v[170:171], v[30:31], v[170:171], v[172:173] neg_lo:[0,0,1] neg_hi:[0,0,1]
	v_pk_fma_f32 v[130:131], v[28:29], v[130:131], v[182:183]
	v_pk_fma_f32 v[128:129], v[30:31], v[128:129], v[180:181]
	v_pk_mul_f32 v[170:171], v[140:141], v[170:171] op_sel_hi:[0,1]
	v_pk_mul_f32 v[172:173], v[140:141], v[174:175] op_sel_hi:[0,1]
	v_pk_mul_f32 v[128:129], v[140:141], v[128:129] op_sel_hi:[0,1]
	v_pk_mul_f32 v[130:131], v[140:141], v[130:131] op_sel_hi:[0,1]
	v_cvt_pk_bf16_f32 v172, v172, v173
	v_cvt_pk_bf16_f32 v173, v170, v171
	v_cvt_pk_bf16_f32 v130, v130, v131
	v_cvt_pk_bf16_f32 v131, v128, v129
	global_store_dwordx2 v[162:163], v[172:173], off
	global_store_dwordx2 v[162:163], v[130:131], off offset:64
	s_nop 1
	v_mov_b32_e32 v128, v184
	v_mov_b32_e32 v129, v185
	v_mov_b32_e32 v130, v186
	v_mov_b32_e32 v131, v187
	v_mov_b32_e32 v170, v188
	v_mov_b32_e32 v171, v189
	v_mov_b32_e32 v172, v190
	v_mov_b32_e32 v173, v191
	v_mov_b32_e32 v174, v129
	v_mov_b32_e32 v175, v131
	v_mov_b32_e32 v176, v171
	v_mov_b32_e32 v177, v173
	v_mov_b32_e32 v171, v172
	v_mov_b32_e32 v129, v130
	v_pk_mul_f32 v[130:131], v[18:19], v[174:175]
	v_pk_mul_f32 v[172:173], v[16:17], v[176:177]
	v_pk_mul_f32 v[178:179], v[18:19], v[128:129]
	v_pk_mul_f32 v[180:181], v[16:17], v[170:171]
	v_pk_fma_f32 v[170:171], v[24:25], v[170:171], v[172:173] neg_lo:[0,0,1] neg_hi:[0,0,1]
	v_pk_fma_f32 v[128:129], v[26:27], v[128:129], v[130:131] neg_lo:[0,0,1] neg_hi:[0,0,1]
	v_pk_fma_f32 v[130:131], v[24:25], v[176:177], v[180:181]
	v_pk_fma_f32 v[172:173], v[26:27], v[174:175], v[178:179]
	v_pk_mul_f32 v[128:129], v[140:141], v[128:129] op_sel_hi:[0,1]
	v_pk_mul_f32 v[170:171], v[140:141], v[170:171] op_sel_hi:[0,1]
	v_pk_mul_f32 v[172:173], v[140:141], v[172:173] op_sel_hi:[0,1]
	v_pk_mul_f32 v[130:131], v[140:141], v[130:131] op_sel_hi:[0,1]
	v_cvt_pk_bf16_f32 v170, v170, v171
	v_cvt_pk_bf16_f32 v171, v128, v129
	v_cvt_pk_bf16_f32 v128, v130, v131
	v_cvt_pk_bf16_f32 v129, v172, v173
	global_store_dwordx2 v[162:163], v[170:171], off offset:8
	global_store_dwordx2 v[162:163], v[128:129], off offset:72
	global_load_dwordx4 v[128:131], v[158:159], off offset:2816
	v_add_u32_e32 v158, 0xb0, v156
	v_ashrrev_i32_e32 v159, 31, v158
	s_and_saveexec_b64 s[60:61], vcc
	s_xor_b64 s[60:61], exec, s[60:61]
	v_add_u32_e32 v140, 0xffff00b0, v156
	v_cmp_gt_u32_e32 vcc, s82, v158
	s_nop 1
	v_cndmask_b32_e32 v140, 0, v140, vcc
	s_andn2_saveexec_b64 s[60:61], s[60:61]
	v_and_b32_e32 v140, 0x7ff, v158
	v_add_u32_e32 v140, 16, v140
	s_or_b64 exec, exec, s[60:61]
	v_lshlrev_b64 v[162:163], 8, v[140:141]
	v_lshl_add_u64 v[162:163], v[142:143], 0, v[162:163]
	global_load_dwordx4 v[170:173], v[162:163], off offset:16
	global_load_dwordx4 v[174:177], v[162:163], off
	global_load_dwordx4 v[184:187], v[162:163], off offset:48
	global_load_dwordx4 v[188:191], v[162:163], off offset:32
	s_waitcnt vmcnt(0)
; __device__ __forceinline__ unsigned cvt_pk_bf16(float lo, float hi) { const cvt_f32x2 v = {lo, hi}; const cvt_bf16x2 b = __builtin_convertvector(v, cvt_bf16x2); return __builtin_bit_cast(unsigned, b); }
; #define EPI_ROWLOOP _Pragma("unroll") for (int ai = 0; ai < 2; ++ai) _Pragma("unroll") for (int m = 0; m < 4; ++m)
;     __device__ __forceinline__ void operator()(const f32x4 (&acc)[2][2][4][2], const Unit& u, int wr, int wc, int fr, int fq) const {
;     ...
;             EPI_ROWLOOP { const int r = row0 + ai * HALF + m * 16; const f32x4 pq = part[r]; const float rs = __builtin_amdgcn_rsqf(((pq[0] + pq[1]) + (pq[2] + pq[3])) * (1.0f / 256.0f) + EP_EPS) * qscale;
;                 const float* t = ropecs + ((size_t)pos_of_row(r) * 32 + 8 * fq) * 2;
;                 bf16_t* rowp = QR + (size_t)r * 512 + (4 * (pn - 4) + wc) * 64 + 8 * fq;
; #pragma unroll
;                 for (int n = 0; n < 2; ++n) { f32x4 a = acc[ai][0][m][n], b = acc[ai][1][m][n]; rope4(a, b, t + 8 * n); a = a * rs; b = b * rs;
;                     *(u32x2*)(rowp + 4 * n) = (u32x2){cvt_pk_bf16(a[0], a[1]), cvt_pk_bf16(a[2], a[3])}; *(u32x2*)(rowp + 32 + 4 * n) = (u32x2){cvt_pk_bf16(b[0], b[1]), cvt_pk_bf16(b[2], b[3])};
;                     asm volatile("" ::: "memory"); } }
	v_add_f32_e32 v128, v128, v129
	v_add_f32_e32 v129, v130, v131
	v_add_f32_e32 v128, v128, v129
	v_fmamk_f32 v128, v128, 0x3b800000, v169
	v_rsq_f32_e32 v130, v128
	v_lshlrev_b64 v[128:129], 10, v[158:159]
	v_lshl_add_u64 v[178:179], v[160:161], 0, v[128:129]
	v_mul_f32_e32 v140, 0x3dd53b94, v130
	v_mov_b32_e32 v128, v171
	v_mov_b32_e32 v129, v173
	v_mov_b32_e32 v130, v175
	v_mov_b32_e32 v131, v177
	v_mov_b32_e32 v175, v176
	v_mov_b32_e32 v171, v172
	v_pk_mul_f32 v[158:159], v[6:7], v[128:129]
	v_pk_mul_f32 v[160:161], v[4:5], v[130:131]
	v_pk_mul_f32 v[172:173], v[6:7], v[170:171]
	v_pk_mul_f32 v[176:177], v[4:5], v[174:175]
	v_pk_fma_f32 v[160:161], v[12:13], v[174:175], v[160:161] neg_lo:[0,0,1] neg_hi:[0,0,1]
	v_pk_fma_f32 v[158:159], v[14:15], v[170:171], v[158:159] neg_lo:[0,0,1] neg_hi:[0,0,1]
	v_pk_fma_f32 v[130:131], v[12:13], v[130:131], v[176:177]
	v_pk_fma_f32 v[128:129], v[14:15], v[128:129], v[172:173]
	v_pk_mul_f32 v[158:159], v[140:141], v[158:159] op_sel_hi:[0,1]
	v_pk_mul_f32 v[160:161], v[140:141], v[160:161] op_sel_hi:[0,1]
	v_pk_mul_f32 v[128:129], v[140:141], v[128:129] op_sel_hi:[0,1]
	v_pk_mul_f32 v[130:131], v[140:141], v[130:131] op_sel_hi:[0,1]
	v_cvt_pk_bf16_f32 v160, v160, v161
	v_cvt_pk_bf16_f32 v161, v158, v159
	v_cvt_pk_bf16_f32 v130, v130, v131
	v_cvt_pk_bf16_f32 v131, v128, v129
	global_store_dwordx2 v[178:179], v[160:161], off
	global_store_dwordx2 v[178:179], v[130:131], off offset:64
	s_nop 1
	v_mov_b32_e32 v128, v184
	v_mov_b32_e32 v129, v185
	v_mov_b32_e32 v130, v186
	v_mov_b32_e32 v131, v187
	v_mov_b32_e32 v158, v188
	v_mov_b32_e32 v159, v189
	v_mov_b32_e32 v160, v190
	v_mov_b32_e32 v161, v191
	v_mov_b32_e32 v162, v129
	v_mov_b32_e32 v163, v131
	v_mov_b32_e32 v170, v159
	v_mov_b32_e32 v171, v161
	v_mov_b32_e32 v159, v160
	v_mov_b32_e32 v129, v130
	v_pk_mul_f32 v[130:131], v[2:3], v[162:163]
	v_pk_mul_f32 v[160:161], v[0:1], v[170:171]
	v_pk_mul_f32 v[172:173], v[2:3], v[128:129]
	v_pk_mul_f32 v[174:175], v[0:1], v[158:159]
	v_pk_fma_f32 v[158:159], v[8:9], v[158:159], v[160:161] neg_lo:[0,0,1] neg_hi:[0,0,1]
	v_pk_fma_f32 v[128:129], v[10:11], v[128:129], v[130:131] neg_lo:[0,0,1] neg_hi:[0,0,1]
	v_pk_fma_f32 v[130:131], v[8:9], v[170:171], v[174:175]
	v_pk_fma_f32 v[160:161], v[10:11], v[162:163], v[172:173]
	v_pk_mul_f32 v[128:129], v[140:141], v[128:129] op_sel_hi:[0,1]
	v_pk_mul_f32 v[158:159], v[140:141], v[158:159] op_sel_hi:[0,1]
	v_pk_mul_f32 v[160:161], v[140:141], v[160:161] op_sel_hi:[0,1]
	v_pk_mul_f32 v[130:131], v[140:141], v[130:131] op_sel_hi:[0,1]
	v_cvt_pk_bf16_f32 v158, v158, v159
	v_cvt_pk_bf16_f32 v159, v128, v129
	v_cvt_pk_bf16_f32 v128, v130, v131
	v_cvt_pk_bf16_f32 v129, v160, v161
	global_store_dwordx2 v[178:179], v[158:159], off offset:8
	global_store_dwordx2 v[178:179], v[128:129], off offset:72
	s_branch .LBB0_540
